# restored original wait-state distances where redundant vmcnt waits were removed (v_add_co->v_addc)
# baseline (speedup 1.0000x reference)
; __device__ __forceinline__ unsigned cvt_pk_bf16(float lo, float hi) { unsigned r; asm volatile("v_cvt_pk_bf16_f32 %0, %1, %2" : "=v"(r) : "v"(lo), "v"(hi)); return r; }
; __device__ __forceinline__ float bflo(unsigned w) { return __uint_as_float(w << 16); }
; __device__ __forceinline__ float bfhi(unsigned w) { return __uint_as_float(w & 0xffff0000u); }
; __global__ void __launch_bounds__(NTHREADS, 2) fwd_kernel(Params P) {
;     ...
;     if (PHON(5)) for (int r = gw; r < MR; r += NGW) {
;         const bf16_t* zr = Z + (size_t)r * NZ + 1024;
;         float v[16]; float s = 0.f;
; #pragma unroll
;         for (int h = 0; h < 2; ++h) { const u32x4 w = *(const u32x4*)(zr + 8 * lane + 512 * h);
;             v[8 * h + 0] = bflo(w.x); v[8 * h + 1] = bfhi(w.x); v[8 * h + 2] = bflo(w.y); v[8 * h + 3] = bfhi(w.y); v[8 * h + 4] = bflo(w.z); v[8 * h + 5] = bfhi(w.z); v[8 * h + 6] = bflo(w.w); v[8 * h + 7] = bfhi(w.w); }
; #pragma unroll
;         for (int j = 0; j < 16; ++j) s += v[j];
;         const float mean = wave_sum(s) * (1.f / BW); float s2 = 0.f;
; #pragma unroll
;         for (int j = 0; j < 16; ++j) { v[j] -= mean; s2 += v[j] * v[j]; }
;         const float rstd = 1.0f / sqrtf(wave_sum(s2) * (1.f / BW) + LN_EPS);
; #pragma unroll
;         for (int h = 0; h < 2; ++h) {
;             const int c0 = 8 * lane + 512 * h; float o[8];
; #pragma unroll
;             for (int j = 0; j < 8; ++j) o[j] = v[8 * h + j] * rstd * P.in[I_GLNG][c0 + j] + P.in[I_GLNB][c0 + j];
;             u32x4 w; w.x = cvt_pk_bf16(o[0], o[1]); w.y = cvt_pk_bf16(o[2], o[3]); w.z = cvt_pk_bf16(o[4], o[5]); w.w = cvt_pk_bf16(o[6], o[7]);
;             *(u32x4*)(VP + (size_t)r * BW + c0) = w;
;             if (r >= MP) { float* ov = out + O_VS + (size_t)(r - MP) * BW + c0; *(f32x4*)ov = (f32x4){o[0], o[1], o[2], o[3]}; *(f32x4*)(ov + 4) = (f32x4){o[4], o[5], o[6], o[7]}; }
.LBB0_573:
	v_lshl_add_u64 v[0:1], s[10:11], 0, v[176:177]
	v_add_co_u32_e32 v4, vcc, 0xeda0000, v0
	s_cmpk_gt_i32 s19, 0x1fff
	s_nop 0
	v_addc_co_u32_e32 v5, vcc, 0, v1, vcc
	global_load_dwordx4 v[0:3], v[4:5], off offset:3072
	s_nop 0
	global_load_dwordx4 v[4:7], v[4:5], off offset:2048
	s_cselect_b64 s[14:15], -1, 0
	s_add_i32 s4, s19, 0xffffe000
	s_lshl_b64 s[0:1], s[4:5], 12
	s_add_u32 s12, s2, s0
	s_addc_u32 s13, s3, s1
	s_cmpk_lt_i32 s19, 0x2000
	s_waitcnt vmcnt(1)
	v_lshlrev_b32_e32 v14, 16, v0
	s_waitcnt vmcnt(0)
	v_lshlrev_b32_e32 v22, 16, v4
	v_and_b32_e32 v15, 0xffff0000, v0
	v_and_b32_e32 v23, 0xffff0000, v4
	v_add_f32_e32 v0, 0, v22
	v_lshlrev_b32_e32 v4, 16, v5
	v_add_f32_e32 v0, v0, v23
	v_and_b32_e32 v5, 0xffff0000, v5
	v_add_f32_e32 v0, v0, v4
	v_lshlrev_b32_e32 v24, 16, v6
	v_add_f32_e32 v0, v0, v5
	v_and_b32_e32 v25, 0xffff0000, v6
	v_add_f32_e32 v0, v0, v24
	v_lshlrev_b32_e32 v6, 16, v7
	v_add_f32_e32 v0, v0, v25
	v_and_b32_e32 v7, 0xffff0000, v7
	v_add_f32_e32 v0, v0, v6
	v_add_f32_e32 v0, v0, v7
	v_add_f32_e32 v0, v0, v14
	v_lshlrev_b32_e32 v16, 16, v1
	v_add_f32_e32 v0, v0, v15
	v_and_b32_e32 v17, 0xffff0000, v1
	v_add_f32_e32 v0, v0, v16
	v_lshlrev_b32_e32 v18, 16, v2
	v_add_f32_e32 v0, v0, v17
	v_and_b32_e32 v19, 0xffff0000, v2
	v_add_f32_e32 v0, v0, v18
	v_lshlrev_b32_e32 v20, 16, v3
	v_add_f32_e32 v0, v0, v19
	v_and_b32_e32 v21, 0xffff0000, v3
	v_add_f32_e32 v0, v0, v20
	v_add_f32_e32 v0, v0, v21
	ds_bpermute_b32 v1, v9, v0
	s_waitcnt lgkmcnt(0)
	v_add_f32_e32 v0, v0, v1
	ds_bpermute_b32 v1, v26, v0
	s_waitcnt lgkmcnt(0)
	v_add_f32_e32 v0, v0, v1
	ds_bpermute_b32 v1, v27, v0
	s_waitcnt lgkmcnt(0)
	v_add_f32_e32 v0, v0, v1
	ds_bpermute_b32 v1, v28, v0
	s_waitcnt lgkmcnt(0)
	v_add_f32_e32 v0, v0, v1
	ds_bpermute_b32 v1, v29, v0
	s_waitcnt lgkmcnt(0)
	v_add_f32_e32 v33, v0, v1
	ds_bpermute_b32 v34, v30, v33
	v_mov_b32_e32 v0, v60
	v_mov_b32_e32 v1, v61
	v_mov_b32_e32 v2, v62
	v_mov_b32_e32 v3, v63
	s_waitcnt lgkmcnt(0)
	v_add_f32_e32 v33, v33, v34
	v_mul_f32_e32 v34, 0x3a800000, v33
	v_pk_add_f32 v[42:43], v[22:23], v[34:35] op_sel_hi:[1,0] neg_lo:[0,1] neg_hi:[0,1]
	v_pk_add_f32 v[44:45], v[4:5], v[34:35] op_sel_hi:[1,0] neg_lo:[0,1] neg_hi:[0,1]
	v_pk_mul_f32 v[4:5], v[42:43], v[42:43]
	v_pk_add_f32 v[48:49], v[6:7], v[34:35] op_sel_hi:[1,0] neg_lo:[0,1] neg_hi:[0,1]
	v_pk_mul_f32 v[6:7], v[44:45], v[44:45]
	v_add_f32_e32 v4, v4, v5
	v_pk_add_f32 v[46:47], v[24:25], v[34:35] op_sel_hi:[1,0] neg_lo:[0,1] neg_hi:[0,1]
	v_add_f32_e32 v4, v4, v6
	v_pk_mul_f32 v[22:23], v[46:47], v[46:47]
	v_add_f32_e32 v4, v4, v7
	v_add_f32_e32 v4, v4, v22
	v_pk_mul_f32 v[24:25], v[48:49], v[48:49]
	v_add_f32_e32 v4, v4, v23
	v_pk_add_f32 v[14:15], v[14:15], v[34:35] op_sel_hi:[1,0] neg_lo:[0,1] neg_hi:[0,1]
	v_add_f32_e32 v4, v4, v24
	v_pk_add_f32 v[16:17], v[16:17], v[34:35] op_sel_hi:[1,0] neg_lo:[0,1] neg_hi:[0,1]
	v_pk_add_f32 v[18:19], v[18:19], v[34:35] op_sel_hi:[1,0] neg_lo:[0,1] neg_hi:[0,1]
	v_pk_add_f32 v[20:21], v[20:21], v[34:35] op_sel_hi:[1,0] neg_lo:[0,1] neg_hi:[0,1]
	v_pk_mul_f32 v[34:35], v[14:15], v[14:15]
	v_add_f32_e32 v4, v4, v25
	v_add_f32_e32 v4, v4, v34
	v_pk_mul_f32 v[36:37], v[16:17], v[16:17]
	v_add_f32_e32 v4, v4, v35
	v_add_f32_e32 v4, v4, v36
	v_pk_mul_f32 v[38:39], v[18:19], v[18:19]
	v_add_f32_e32 v4, v4, v37
	v_add_f32_e32 v4, v4, v38
	v_pk_mul_f32 v[40:41], v[20:21], v[20:21]
	v_add_f32_e32 v4, v4, v39
	v_add_f32_e32 v4, v4, v40
	v_add_f32_e32 v22, v4, v41
	v_mov_b32_e32 v4, v64
	v_mov_b32_e32 v5, v65
	v_mov_b32_e32 v6, v66
	v_mov_b32_e32 v7, v67
	v_mov_b32_e32 v34, v68
	v_mov_b32_e32 v35, v69
	v_mov_b32_e32 v36, v70
	v_mov_b32_e32 v37, v71
	v_mov_b32_e32 v38, v72
	v_mov_b32_e32 v39, v73
	v_mov_b32_e32 v40, v74
	v_mov_b32_e32 v41, v75
	ds_bpermute_b32 v23, v9, v22
	s_waitcnt lgkmcnt(0)
	v_add_f32_e32 v22, v22, v23
	ds_bpermute_b32 v23, v26, v22
	s_waitcnt lgkmcnt(0)
	v_add_f32_e32 v22, v22, v23
	ds_bpermute_b32 v23, v27, v22
	s_waitcnt lgkmcnt(0)
	v_add_f32_e32 v22, v22, v23
	ds_bpermute_b32 v23, v28, v22
	s_waitcnt lgkmcnt(0)
	v_add_f32_e32 v22, v22, v23
	ds_bpermute_b32 v23, v29, v22
	s_waitcnt lgkmcnt(0)
	v_add_f32_e32 v24, v22, v23
	ds_bpermute_b32 v25, v30, v24
	v_lshl_add_u64 v[22:23], s[6:7], 0, v[176:177]
	s_waitcnt lgkmcnt(0)
	v_add_f32_e32 v24, v24, v25
	v_fmamk_f32 v24, v24, 0x3a800000, v31
	v_mul_f32_e32 v25, 0x4f800000, v24
	v_cmp_gt_f32_e32 vcc, s18, v24
	s_nop 1
	v_cndmask_b32_e32 v24, v24, v25, vcc
	v_sqrt_f32_e32 v25, v24
	s_nop 0
	v_add_u32_e32 v33, -1, v25
	v_add_u32_e32 v50, 1, v25
	v_fma_f32 v51, -v33, v25, v24
	v_fma_f32 v52, -v50, v25, v24
	v_cmp_ge_f32_e64 s[0:1], 0, v51
	s_nop 1
	v_cndmask_b32_e64 v25, v25, v33, s[0:1]
	v_cmp_lt_f32_e64 s[0:1], 0, v52
	s_nop 1
	v_cndmask_b32_e64 v25, v25, v50, s[0:1]
	v_mul_f32_e32 v33, 0x37800000, v25
	v_cndmask_b32_e32 v25, v25, v33, vcc
	v_cmp_class_f32_e32 vcc, v24, v32
	s_nop 1
	v_cndmask_b32_e32 v24, v25, v24, vcc
	v_div_scale_f32 v25, s[0:1], v24, v24, 1.0
	v_rcp_f32_e32 v33, v25
	v_div_scale_f32 v50, vcc, 1.0, v24, 1.0
	v_fma_f32 v51, -v25, v33, 1.0
	v_fmac_f32_e32 v33, v51, v33
	v_mul_f32_e32 v51, v50, v33
	v_fma_f32 v52, -v25, v51, v50
	v_fmac_f32_e32 v51, v52, v33
	v_fma_f32 v25, -v25, v51, v50
	v_div_fmas_f32 v25, v25, v33, v51
	v_div_fixup_f32 v24, v25, v24, 1.0
	v_add_co_u32_e32 v50, vcc, 0x22720000, v22
	v_pk_mul_f32 v[42:43], v[24:25], v[42:43] op_sel_hi:[0,1]
	v_pk_mul_f32 v[44:45], v[24:25], v[44:45] op_sel_hi:[0,1]
	v_pk_mul_f32 v[46:47], v[24:25], v[46:47] op_sel_hi:[0,1]
	v_pk_mul_f32 v[48:49], v[24:25], v[48:49] op_sel_hi:[0,1]
	v_addc_co_u32_e32 v51, vcc, 0, v23, vcc
	s_nop 0
	v_pk_fma_f32 v[4:5], v[42:43], v[4:5], v[0:1]
	v_pk_fma_f32 v[6:7], v[44:45], v[6:7], v[2:3]
	s_nop 0
	v_pk_fma_f32 v[0:1], v[46:47], v[34:35], v[38:39]
	v_pk_fma_f32 v[2:3], v[48:49], v[36:37], v[40:41]
	v_lshlrev_b32_e32 v33, 2, v8
	v_cvt_pk_bf16_f32 v34, v4, v5
	v_cvt_pk_bf16_f32 v35, v6, v7
	v_cvt_pk_bf16_f32 v36, v0, v1
	v_cvt_pk_bf16_f32 v37, v2, v3
	global_store_dwordx4 v[50:51], v[34:37], off
	s_cbranch_scc1 .LBB0_575
	global_store_dwordx4 v33, v[4:7], s[12:13]
	global_store_dwordx4 v33, v[0:3], s[12:13] offset:16
; __device__ __forceinline__ unsigned cvt_pk_bf16(float lo, float hi) { unsigned r; asm volatile("v_cvt_pk_bf16_f32 %0, %1, %2" : "=v"(r) : "v"(lo), "v"(hi)); return r; }
; __global__ void __launch_bounds__(NTHREADS, 2) fwd_kernel(Params P) {
;     ...
;         for (int h = 0; h < 2; ++h) {
;             const int c0 = 8 * lane + 512 * h; float o[8];
; #pragma unroll
;             for (int j = 0; j < 8; ++j) o[j] = v[8 * h + j] * rstd * P.in[I_GLNG][c0 + j] + P.in[I_GLNB][c0 + j];
;             u32x4 w; w.x = cvt_pk_bf16(o[0], o[1]); w.y = cvt_pk_bf16(o[2], o[3]); w.z = cvt_pk_bf16(o[4], o[5]); w.w = cvt_pk_bf16(o[6], o[7]);
;             *(u32x4*)(VP + (size_t)r * BW + c0) = w;
;             if (r >= MP) { float* ov = out + O_VS + (size_t)(r - MP) * BW + c0; *(f32x4*)ov = (f32x4){o[0], o[1], o[2], o[3]}; *(f32x4*)(ov + 4) = (f32x4){o[4], o[5], o[6], o[7]}; }
.LBB0_575:
	s_nop 1
	v_mov_b32_e32 v0, v76
	v_mov_b32_e32 v1, v77
	v_mov_b32_e32 v2, v78
	v_mov_b32_e32 v3, v79
	s_nop 0
	v_mov_b32_e32 v4, v80
	v_mov_b32_e32 v5, v81
	v_mov_b32_e32 v6, v82
	v_mov_b32_e32 v7, v83
	v_mov_b32_e32 v34, v84
	v_mov_b32_e32 v35, v85
	v_mov_b32_e32 v36, v86
	v_mov_b32_e32 v37, v87
	v_mov_b32_e32 v38, v88
	v_mov_b32_e32 v39, v89
	v_mov_b32_e32 v40, v90
	v_mov_b32_e32 v41, v91
	v_mov_b32_e32 v25, v24
	v_add_co_u32_e32 v22, vcc, 0x22720000, v22
	v_pk_mul_f32 v[14:15], v[24:25], v[14:15]
	v_pk_mul_f32 v[16:17], v[24:25], v[16:17]
	v_pk_mul_f32 v[18:19], v[24:25], v[18:19]
	v_pk_mul_f32 v[20:21], v[24:25], v[20:21]
	v_addc_co_u32_e32 v23, vcc, 0, v23, vcc
	s_andn2_b64 vcc, exec, s[14:15]
	s_nop 0
	v_pk_fma_f32 v[4:5], v[14:15], v[4:5], v[0:1]
	v_pk_fma_f32 v[6:7], v[16:17], v[6:7], v[2:3]
	s_nop 0
	v_pk_fma_f32 v[0:1], v[18:19], v[34:35], v[38:39]
	v_pk_fma_f32 v[2:3], v[20:21], v[36:37], v[40:41]
	v_cvt_pk_bf16_f32 v14, v4, v5
	v_cvt_pk_bf16_f32 v15, v6, v7
	v_cvt_pk_bf16_f32 v16, v0, v1
	s_nop 0
	v_cvt_pk_bf16_f32 v17, v2, v3
	global_store_dwordx4 v[22:23], v[14:17], off offset:1024
	s_cbranch_vccnz .LBB0_572
	global_store_dwordx4 v33, v[4:7], s[12:13] offset:2048
	global_store_dwordx4 v33, v[0:3], s[12:13] offset:2064
	s_branch .LBB0_572

; __device__ __forceinline__ void ln_row(const float* yrow, const float* g, const float* b, float* of, bf16_t* ob, int lane) {
;     f32x4 v[8]; float s = 0.f;
; #pragma unroll
;     for (int j = 0; j < 8; ++j) { v[j] = *(const f32x4*)(yrow + 4 * lane + 256 * j); s += (v[j][0] + v[j][1]) + (v[j][2] + v[j][3]); }
;     const float mean = wave_sum(s) * (1.f / D); float s2 = 0.f;
; #pragma unroll
;     for (int j = 0; j < 8; ++j) { v[j] = v[j] - mean; s2 += (v[j][0] * v[j][0] + v[j][1] * v[j][1]) + (v[j][2] * v[j][2] + v[j][3] * v[j][3]); }
;     const float rstd = 1.0f / sqrtf(wave_sum(s2) * (1.f / D) + LN_EPS);
.LBB0_1182:
	v_lshl_add_u64 v[16:17], s[4:5], 0, v[176:177]
	v_add_co_u32_e32 v18, vcc, s10, v16
	s_nop 1
	v_addc_co_u32_e32 v19, vcc, 0, v17, vcc
	v_add_co_u32_e32 v60, vcc, 0x1a320000, v16
	global_load_dwordx4 v[8:11], v[18:19], off
	global_load_dwordx4 v[12:15], v[18:19], off offset:1024
	global_load_dwordx4 v[4:7], v[18:19], off offset:2048
	global_load_dwordx4 v[0:3], v[18:19], off offset:3072
	s_waitcnt lgkmcnt(0)
	v_addc_co_u32_e32 v61, vcc, 0, v17, vcc
	global_load_dwordx4 v[28:31], v[60:61], off
	global_load_dwordx4 v[24:27], v[60:61], off offset:1024
	global_load_dwordx4 v[20:23], v[60:61], off offset:2048
	global_load_dwordx4 v[16:19], v[60:61], off offset:3072
	s_and_b64 vcc, exec, s[0:1]
	s_waitcnt vmcnt(7)
	v_mov_b32_e32 v63, v10
	s_waitcnt vmcnt(6)
	v_mov_b32_e32 v66, v13
	v_mov_b32_e32 v67, v14
	v_mov_b32_e32 v68, v12
	v_mov_b32_e32 v69, v15
	s_waitcnt vmcnt(5)
	v_add_f32_e32 v70, v4, v5
	v_add_f32_e32 v72, v6, v7
	s_waitcnt vmcnt(4)
	v_mov_b32_e32 v71, v2
	v_mov_b32_e32 v73, v3
	s_waitcnt vmcnt(3)
	v_mov_b32_e32 v74, v28
	s_waitcnt vmcnt(2)
	v_mov_b32_e32 v75, v24
	v_mov_b32_e32 v76, v29
	v_mov_b32_e32 v77, v25
	v_mov_b32_e32 v78, v30
	v_mov_b32_e32 v79, v26
	v_mov_b32_e32 v80, v31
	v_mov_b32_e32 v81, v27
	v_mov_b32_e32 v65, v11
	s_waitcnt vmcnt(1)
	v_mov_b32_e32 v82, v21
	v_mov_b32_e32 v83, v22
	v_mov_b32_e32 v84, v20
	v_mov_b32_e32 v85, v23
	s_waitcnt vmcnt(0)
	v_add_f32_e32 v62, v16, v17
	v_add_f32_e32 v64, v18, v19
	v_pk_add_f32 v[66:67], v[66:67], v[68:69]
	v_pk_add_f32 v[68:69], v[70:71], v[72:73]
	v_pk_add_f32 v[70:71], v[74:75], v[76:77]
	v_pk_add_f32 v[72:73], v[78:79], v[80:81]
	v_pk_add_f32 v[74:75], v[82:83], v[84:85]
	v_pk_add_f32 v[62:63], v[62:63], v[64:65]
	v_pk_add_f32 v[64:65], v[66:67], v[66:67] op_sel:[0,1] op_sel_hi:[1,0]
	v_pk_add_f32 v[66:67], v[70:71], v[72:73]
	v_pk_add_f32 v[70:71], v[74:75], v[74:75] op_sel:[0,1] op_sel_hi:[1,0]
	v_add_f32_e32 v60, 0, v66
	v_mov_b32_e32 v61, v8
	v_mov_b32_e32 v71, v9
	v_add_f32_e32 v60, v60, v67
	v_pk_add_f32 v[60:61], v[60:61], v[70:71]
	v_mov_b32_e32 v65, v1
	v_pk_add_f32 v[60:61], v[60:61], v[62:63]
	s_nop 0
	v_pk_add_f32 v[60:61], v[60:61], v[60:61] op_sel:[0,1] op_sel_hi:[1,0]
	s_nop 0
	v_mov_b32_e32 v61, v0
	v_pk_add_f32 v[60:61], v[60:61], v[64:65]
	s_nop 0
	v_pk_add_f32 v[60:61], v[60:61], v[68:69]
	s_nop 0
	v_add_f32_e32 v60, v60, v61
	ds_bpermute_b32 v61, v52, v60
	s_waitcnt lgkmcnt(0)
	v_add_f32_e32 v60, v60, v61
	ds_bpermute_b32 v61, v53, v60
	s_waitcnt lgkmcnt(0)
	v_add_f32_e32 v60, v60, v61
	ds_bpermute_b32 v61, v54, v60
	s_waitcnt lgkmcnt(0)
	v_add_f32_e32 v60, v60, v61
	ds_bpermute_b32 v61, v55, v60
	s_waitcnt lgkmcnt(0)
	v_add_f32_e32 v60, v60, v61
	ds_bpermute_b32 v61, v56, v60
	s_waitcnt lgkmcnt(0)
	v_add_f32_e32 v60, v60, v61
	ds_bpermute_b32 v61, v57, v60
	s_waitcnt lgkmcnt(0)
	v_add_f32_e32 v60, v60, v61
	v_fmamk_f32 v31, v60, 0xba000000, v31
	v_fmamk_f32 v29, v60, 0xba000000, v29
	v_fmamk_f32 v27, v60, 0xba000000, v27
	v_fmamk_f32 v25, v60, 0xba000000, v25
	v_fmamk_f32 v30, v60, 0xba000000, v30
	v_fmac_f32_e32 v28, 0xba000000, v60
	v_fmamk_f32 v26, v60, 0xba000000, v26
	v_fmac_f32_e32 v24, 0xba000000, v60
	v_fmamk_f32 v23, v60, 0xba000000, v23
	v_fmamk_f32 v21, v60, 0xba000000, v21
	v_mul_f32_e32 v61, v29, v29
	v_mul_f32_e32 v62, v31, v31
	v_mul_f32_e32 v63, v25, v25
	v_mul_f32_e32 v64, v27, v27
	v_fmamk_f32 v22, v60, 0xba000000, v22
	v_fmac_f32_e32 v20, 0xba000000, v60
	v_fmamk_f32 v19, v60, 0xba000000, v19
	v_fmamk_f32 v17, v60, 0xba000000, v17
	v_mul_f32_e32 v65, v21, v21
	v_mul_f32_e32 v66, v23, v23
	v_fmac_f32_e32 v61, v28, v28
	v_fmac_f32_e32 v62, v30, v30
	v_fmac_f32_e32 v63, v24, v24
	v_fmac_f32_e32 v64, v26, v26
	v_fmamk_f32 v18, v60, 0xba000000, v18
	v_fmac_f32_e32 v16, 0xba000000, v60
	v_fmamk_f32 v11, v60, 0xba000000, v11
	v_fmamk_f32 v9, v60, 0xba000000, v9
	v_mul_f32_e32 v67, v17, v17
	v_mul_f32_e32 v68, v19, v19
	v_fmac_f32_e32 v65, v20, v20
	v_fmac_f32_e32 v66, v22, v22
	v_add_f32_e32 v61, v61, v62
	v_add_f32_e32 v62, v63, v64
	v_fmamk_f32 v10, v60, 0xba000000, v10
	v_fmac_f32_e32 v8, 0xba000000, v60
	v_fmamk_f32 v15, v60, 0xba000000, v15
	v_fmamk_f32 v13, v60, 0xba000000, v13
	v_mul_f32_e32 v69, v9, v9
	v_mul_f32_e32 v70, v11, v11
	v_fmac_f32_e32 v67, v16, v16
	v_fmac_f32_e32 v68, v18, v18
	v_add_f32_e32 v63, v65, v66
	v_add_f32_e32 v61, v61, v62
	v_fmamk_f32 v14, v60, 0xba000000, v14
	v_fmac_f32_e32 v12, 0xba000000, v60
	v_fmamk_f32 v7, v60, 0xba000000, v7
	v_fmamk_f32 v5, v60, 0xba000000, v5
	v_mul_f32_e32 v71, v13, v13
	v_mul_f32_e32 v72, v15, v15
	v_fmac_f32_e32 v69, v8, v8
	v_fmac_f32_e32 v70, v10, v10
	v_add_f32_e32 v64, v67, v68
	v_add_f32_e32 v61, v63, v61
	v_fmamk_f32 v6, v60, 0xba000000, v6
	v_fmac_f32_e32 v4, 0xba000000, v60
	v_mul_f32_e32 v73, v5, v5
	v_fmac_f32_e32 v71, v12, v12
	v_fmac_f32_e32 v72, v14, v14
	v_add_f32_e32 v65, v69, v70
	v_add_f32_e32 v61, v64, v61
	v_mul_f32_e32 v62, v7, v7
	v_fmac_f32_e32 v73, v4, v4
	v_add_f32_e32 v66, v71, v72
	v_add_f32_e32 v61, v65, v61
	v_fmac_f32_e32 v62, v6, v6
	v_add_f32_e32 v61, v66, v61
	v_add_f32_e32 v62, v73, v62
	v_fmamk_f32 v3, v60, 0xba000000, v3
	v_fmamk_f32 v1, v60, 0xba000000, v1
	v_add_f32_e32 v61, v62, v61
	v_fmamk_f32 v2, v60, 0xba000000, v2
	v_fmac_f32_e32 v0, 0xba000000, v60
	v_mul_f32_e32 v60, v1, v1
	v_mul_f32_e32 v62, v3, v3
	v_fmac_f32_e32 v60, v0, v0
	v_fmac_f32_e32 v62, v2, v2
	v_add_f32_e32 v60, v60, v62
	v_add_f32_e32 v60, v60, v61
	ds_bpermute_b32 v61, v52, v60
	s_waitcnt lgkmcnt(0)
	v_add_f32_e32 v60, v60, v61
	ds_bpermute_b32 v61, v53, v60
	s_waitcnt lgkmcnt(0)
	v_add_f32_e32 v60, v60, v61
	ds_bpermute_b32 v61, v54, v60
	s_waitcnt lgkmcnt(0)
	v_add_f32_e32 v60, v60, v61
	ds_bpermute_b32 v61, v55, v60
	s_waitcnt lgkmcnt(0)
	v_add_f32_e32 v60, v60, v61
	ds_bpermute_b32 v61, v56, v60
	s_waitcnt lgkmcnt(0)
	v_add_f32_e32 v60, v60, v61
	ds_bpermute_b32 v61, v57, v60
	s_cbranch_vccnz .LBB0_1181
; __device__ __forceinline__ unsigned cvt_pk_bf16(float lo, float hi) { unsigned r; asm volatile("v_cvt_pk_bf16_f32 %0, %1, %2" : "=v"(r) : "v"(lo), "v"(hi)); return r; }
; __device__ __forceinline__ void ln_row(const float* yrow, const float* g, const float* b, float* of, bf16_t* ob, int lane) {
;     ...
;     const float rstd = 1.0f / sqrtf(wave_sum(s2) * (1.f / D) + LN_EPS);
; #pragma unroll
;     for (int j = 0; j < 8; ++j) {
;         const f32x4 gg = *(const f32x4*)(g + 4 * lane + 256 * j), bb = *(const f32x4*)(b + 4 * lane + 256 * j);
;         const f32x4 o = v[j] * rstd * gg + bb;
;         if (of) __builtin_nontemporal_store(o, (f32x4*)(of + 4 * lane + 256 * j));
;         if (ob) { u32x2 w; w.x = cvt_pk_bf16(o[0], o[1]); w.y = cvt_pk_bf16(o[2], o[3]); *(u32x2*)(ob + 4 * lane + 256 * j) = w; }
;     }
	v_mov_b32_e32 v62, v100
	v_mov_b32_e32 v63, v101
	v_mov_b32_e32 v64, v102
	v_mov_b32_e32 v65, v103
	v_mov_b32_e32 v66, v104
	v_mov_b32_e32 v67, v105
	v_mov_b32_e32 v68, v106
	v_mov_b32_e32 v69, v107
	s_waitcnt lgkmcnt(0)
	v_add_f32_e32 v60, v60, v61
	v_fmamk_f32 v60, v60, 0x3a000000, v58
	v_mul_f32_e32 v61, 0x4f800000, v60
	v_cmp_gt_f32_e32 vcc, s11, v60
	s_nop 1
	v_cndmask_b32_e32 v60, v60, v61, vcc
	v_sqrt_f32_e32 v61, v60
	s_nop 0
	v_add_u32_e32 v70, -1, v61
	v_add_u32_e32 v71, 1, v61
	v_fma_f32 v72, -v70, v61, v60
	v_fma_f32 v73, -v71, v61, v60
	v_cmp_ge_f32_e64 s[2:3], 0, v72
	s_nop 1
	v_cndmask_b32_e64 v61, v61, v70, s[2:3]
	v_cmp_lt_f32_e64 s[2:3], 0, v73
	s_nop 1
	v_cndmask_b32_e64 v61, v61, v71, s[2:3]
	v_mul_f32_e32 v70, 0x37800000, v61
	v_cndmask_b32_e32 v61, v61, v70, vcc
	v_cmp_class_f32_e32 vcc, v60, v59
	v_lshl_add_u64 v[70:71], s[8:9], 0, v[176:177]
	s_nop 0
	v_cndmask_b32_e32 v60, v61, v60, vcc
	v_div_scale_f32 v61, s[2:3], v60, v60, 1.0
	v_rcp_f32_e32 v72, v61
	v_div_scale_f32 v73, vcc, 1.0, v60, 1.0
	v_fma_f32 v74, -v61, v72, 1.0
	v_fmac_f32_e32 v72, v74, v72
	v_mul_f32_e32 v74, v73, v72
	v_fma_f32 v75, -v61, v74, v73
	v_fmac_f32_e32 v74, v75, v72
	v_fma_f32 v61, -v61, v74, v73
	v_div_fmas_f32 v61, v61, v72, v74
	v_div_fixup_f32 v72, v61, v60, 1.0
	v_pk_mul_f32 v[28:29], v[28:29], v[72:73] op_sel_hi:[1,0]
	v_pk_mul_f32 v[30:31], v[30:31], v[72:73] op_sel_hi:[1,0]
	v_pk_mul_f32 v[26:27], v[26:27], v[72:73] op_sel_hi:[1,0]
	v_pk_mul_f32 v[24:25], v[24:25], v[72:73] op_sel_hi:[1,0]
	v_pk_mul_f32 v[22:23], v[22:23], v[72:73] op_sel_hi:[1,0]
	v_pk_mul_f32 v[20:21], v[20:21], v[72:73] op_sel_hi:[1,0]
	v_pk_mul_f32 v[18:19], v[18:19], v[72:73] op_sel_hi:[1,0]
	v_pk_mul_f32 v[16:17], v[16:17], v[72:73] op_sel_hi:[1,0]
	v_pk_mul_f32 v[10:11], v[10:11], v[72:73] op_sel_hi:[1,0]
	v_pk_mul_f32 v[8:9], v[8:9], v[72:73] op_sel_hi:[1,0]
	v_pk_mul_f32 v[14:15], v[14:15], v[72:73] op_sel_hi:[1,0]
	v_pk_mul_f32 v[12:13], v[12:13], v[72:73] op_sel_hi:[1,0]
	v_pk_mul_f32 v[6:7], v[6:7], v[72:73] op_sel_hi:[1,0]
	v_pk_mul_f32 v[4:5], v[4:5], v[72:73] op_sel_hi:[1,0]
	v_pk_mul_f32 v[2:3], v[2:3], v[72:73] op_sel_hi:[1,0]
	v_pk_mul_f32 v[0:1], v[0:1], v[72:73] op_sel_hi:[1,0]
	s_nop 0
	v_pk_fma_f32 v[30:31], v[30:31], v[64:65], v[68:69]
	v_pk_fma_f32 v[28:29], v[28:29], v[62:63], v[66:67]
	global_store_dwordx4 v[70:71], v[28:31], off nt
	s_nop 1
	v_mov_b32_e32 v28, v108
	v_mov_b32_e32 v29, v109
	v_mov_b32_e32 v30, v110
	v_mov_b32_e32 v31, v111
	v_mov_b32_e32 v60, v112
	v_mov_b32_e32 v61, v113
	v_mov_b32_e32 v62, v114
	v_mov_b32_e32 v63, v115
	s_nop 0
	v_pk_fma_f32 v[24:25], v[24:25], v[28:29], v[60:61]
	v_pk_fma_f32 v[26:27], v[26:27], v[30:31], v[62:63]
	global_store_dwordx4 v[70:71], v[24:27], off offset:1024 nt
	s_nop 1
	v_mov_b32_e32 v24, v116
	v_mov_b32_e32 v25, v117
	v_mov_b32_e32 v26, v118
	v_mov_b32_e32 v27, v119
	v_mov_b32_e32 v28, v120
	v_mov_b32_e32 v29, v121
	v_mov_b32_e32 v30, v122
	v_mov_b32_e32 v31, v123
	s_nop 0
	v_pk_fma_f32 v[20:21], v[20:21], v[24:25], v[28:29]
	v_pk_fma_f32 v[22:23], v[22:23], v[26:27], v[30:31]
	global_store_dwordx4 v[70:71], v[20:23], off offset:2048 nt
	s_nop 1
	v_mov_b32_e32 v20, v124
	v_mov_b32_e32 v21, v125
	v_mov_b32_e32 v22, v126
	v_mov_b32_e32 v23, v127
	v_mov_b32_e32 v24, v128
	v_mov_b32_e32 v25, v129
	v_mov_b32_e32 v26, v130
	v_mov_b32_e32 v27, v131
	s_nop 0
	v_pk_fma_f32 v[16:17], v[16:17], v[20:21], v[24:25]
	v_pk_fma_f32 v[18:19], v[18:19], v[22:23], v[26:27]
	global_store_dwordx4 v[70:71], v[16:19], off offset:3072 nt
	s_nop 1
	v_mov_b32_e32 v16, v132
	v_mov_b32_e32 v17, v133
	v_mov_b32_e32 v18, v134
	v_mov_b32_e32 v19, v135
	v_mov_b32_e32 v20, v136
	v_mov_b32_e32 v21, v137
	v_mov_b32_e32 v22, v138
	v_mov_b32_e32 v23, v139
	v_add_co_u32_e32 v24, vcc, s12, v70
	s_nop 0
	v_pk_fma_f32 v[8:9], v[8:9], v[16:17], v[20:21]
	v_addc_co_u32_e32 v25, vcc, 0, v71, vcc
	v_pk_fma_f32 v[10:11], v[10:11], v[18:19], v[22:23]
	global_store_dwordx4 v[24:25], v[8:11], off nt
	s_nop 1
	v_mov_b32_e32 v8, v140
	v_mov_b32_e32 v9, v141
	v_mov_b32_e32 v10, v142
	v_mov_b32_e32 v11, v143
	v_mov_b32_e32 v16, v144
	v_mov_b32_e32 v17, v145
	v_mov_b32_e32 v18, v146
	v_mov_b32_e32 v19, v147
	s_nop 0
	v_pk_fma_f32 v[8:9], v[12:13], v[8:9], v[16:17]
	v_pk_fma_f32 v[10:11], v[14:15], v[10:11], v[18:19]
	global_store_dwordx4 v[24:25], v[8:11], off offset:1024 nt
	s_nop 1
	v_mov_b32_e32 v8, v148
	v_mov_b32_e32 v9, v149
	v_mov_b32_e32 v10, v150
	v_mov_b32_e32 v11, v151
	v_mov_b32_e32 v12, v152
	v_mov_b32_e32 v13, v153
	v_mov_b32_e32 v14, v154
	v_mov_b32_e32 v15, v155
	s_nop 0
	v_pk_fma_f32 v[4:5], v[4:5], v[8:9], v[12:13]
	v_pk_fma_f32 v[6:7], v[6:7], v[10:11], v[14:15]
	global_store_dwordx4 v[24:25], v[4:7], off offset:2048 nt
	s_nop 1
	v_mov_b32_e32 v4, v156
	v_mov_b32_e32 v5, v157
	v_mov_b32_e32 v6, v158
	v_mov_b32_e32 v7, v159
	v_mov_b32_e32 v8, v160
	v_mov_b32_e32 v9, v161
	v_mov_b32_e32 v10, v162
	v_mov_b32_e32 v11, v163
	s_nop 0
	v_pk_fma_f32 v[0:1], v[0:1], v[4:5], v[8:9]
	v_pk_fma_f32 v[2:3], v[2:3], v[6:7], v[10:11]
	global_store_dwordx4 v[24:25], v[0:3], off offset:3072 nt
	s_nop 1
	s_branch .LBB0_1181
